# phase 0 row items: prefetch next item's x/g/pos loads during current item's body
# baseline (speedup 1.0000x reference)
.LBB0_15:
	s_cmpk_gt_i32 s2, 0x371f
	s_cbranch_scc1 .LBB0_55
	v_writelane_b32 v252, 0, 44
	v_and_b32_e32 v17, 63, v2
	v_lshlrev_b32_e32 v1, 1, v17
	v_cvt_f32_ubyte0_e32 v1, v1
	v_mul_f32_e32 v1, 0x3c800000, v1
	v_mov_b32_e32 v4, 0x461c4000
	v_cmp_eq_f32_e32 vcc, 0, v1
	s_mov_b32 s3, 0x3f2aaaab
	s_mov_b32 s4, 0x42b17218
	v_cndmask_b32_e64 v14, v4, 1.0, vcc
	v_frexp_mant_f32_e32 v4, v14
	v_cmp_gt_f32_e32 vcc, s3, v4
	s_mov_b32 s3, 0x3f317218
	s_mov_b32 s5, 0x3fb8aa3b
	v_cndmask_b32_e64 v5, 1.0, 2.0, vcc
	v_mul_f32_e32 v4, v4, v5
	v_add_f32_e32 v7, 1.0, v4
	v_rcp_f32_e32 v12, v7
	v_add_f32_e32 v5, -1.0, v7
	v_sub_f32_e32 v9, v4, v5
	v_add_f32_e32 v5, -1.0, v4
	v_mul_f32_e32 v13, v5, v12
	v_mul_f32_e32 v6, v7, v13
	v_fma_f32 v8, v13, v7, -v6
	v_fmac_f32_e32 v8, v13, v9
	v_add_f32_e32 v4, v6, v8
	v_sub_f32_e32 v7, v5, v4
	v_pk_add_f32 v[10:11], v[4:5], v[6:7] neg_lo:[0,1] neg_hi:[0,1]
	v_mov_b32_e32 v9, v4
	v_pk_add_f32 v[4:5], v[10:11], v[8:9] neg_lo:[0,1] neg_hi:[0,1]
	v_mov_b32_e32 v8, 0x3e91f4c4
	v_add_f32_e32 v4, v4, v5
	v_add_f32_e32 v4, v7, v4
	v_mul_f32_e32 v5, v12, v4
	v_add_f32_e32 v4, v13, v5
	v_sub_f32_e32 v6, v4, v13
	v_sub_f32_e32 v15, v5, v6
	v_mul_f32_e32 v5, v4, v4
	v_fma_f32 v7, v4, v4, -v5
	v_add_f32_e32 v6, v15, v15
	v_fmac_f32_e32 v7, v4, v6
	v_add_f32_e32 v6, v5, v7
	v_fmac_f32_e32 v8, 0x3e76c4e1, v6
	v_fmaak_f32 v8, v6, v8, 0x3ecccdef
	v_sub_f32_e32 v5, v6, v5
	v_sub_f32_e32 v16, v7, v5
	v_mul_f32_e32 v5, v6, v8
	v_fma_f32 v7, v6, v8, -v5
	v_fmac_f32_e32 v7, v16, v8
	v_add_f32_e32 v8, v5, v7
	v_add_f32_e32 v9, 0x3f2aaaaa, v8
	v_sub_f32_e32 v5, v8, v5
	v_sub_f32_e32 v5, v7, v5
	v_add_f32_e32 v7, 0xbf2aaaaa, v9
	v_add_f32_e32 v5, 0x31739010, v5
	v_sub_f32_e32 v7, v8, v7
	v_pk_mul_f32 v[10:11], v[4:5], v[6:7]
	v_pk_add_f32 v[12:13], v[4:5], v[6:7]
	v_fma_f32 v8, v6, v4, -v10
	v_fmac_f32_e32 v8, v6, v15
	v_mov_b32_e32 v11, v13
	v_fmac_f32_e32 v8, v16, v4
	v_pk_add_f32 v[6:7], v[10:11], v[8:9]
	v_ldexp_f32 v16, v15, 1
	v_sub_f32_e32 v5, v6, v10
	v_sub_f32_e32 v5, v8, v5
	v_sub_f32_e32 v8, v9, v7
	v_add_f32_e32 v11, v13, v8
	v_pk_mul_f32 v[8:9], v[6:7], v[6:7] op_sel:[0,1] op_sel_hi:[1,0]
	v_cvt_f64_f32_e32 v[12:13], v14
	v_frexp_exp_i32_f64_e32 v9, v[12:13]
	v_subbrev_co_u32_e32 v9, vcc, 0, v9, vcc
	v_cvt_f32_i32_e32 v9, v9
	v_fma_f32 v10, v6, v7, -v8
	v_fmac_f32_e32 v10, v6, v11
	v_fmac_f32_e32 v10, v5, v7
	v_mul_f32_e32 v6, 0x3f317218, v9
	v_fma_f32 v5, v9, s3, -v6
	v_fmamk_f32 v12, v9, 0xb102e308, v5
	v_ldexp_f32 v13, v4, 1
	v_add_f32_e32 v7, v8, v10
	v_pk_add_f32 v[4:5], v[6:7], v[12:13]
	v_mov_b32_e32 v14, v7
	v_mov_b32_e32 v15, v5
	v_mov_b32_e32 v9, v13
	v_pk_add_f32 v[8:9], v[14:15], v[8:9] neg_lo:[0,1] neg_hi:[0,1]
	v_mov_b32_e32 v11, v7
	v_pk_add_f32 v[8:9], v[10:11], v[8:9] neg_lo:[0,1] neg_hi:[0,1]
	v_mov_b32_e32 v13, v4
	v_add_f32_e32 v7, v16, v8
	v_add_f32_e32 v7, v7, v9
	v_pk_add_f32 v[8:9], v[4:5], v[6:7] neg_lo:[0,1] neg_hi:[0,1]
	v_pk_add_f32 v[10:11], v[4:5], v[6:7]
	v_mov_b32_e32 v6, v7
	v_mov_b32_e32 v9, v11
	v_pk_add_f32 v[14:15], v[12:13], v[8:9] neg_lo:[0,1] neg_hi:[0,1]
	v_pk_add_f32 v[8:9], v[12:13], v[8:9]
	v_mov_b32_e32 v7, v4
	v_pk_add_f32 v[12:13], v[8:9], v[4:5] op_sel:[1,0] op_sel_hi:[0,1] neg_lo:[0,1] neg_hi:[0,1]
	v_pk_add_f32 v[18:19], v[10:11], v[12:13] op_sel_hi:[1,0] neg_lo:[0,1] neg_hi:[0,1]
	v_mov_b32_e32 v10, v11
	v_mov_b32_e32 v11, v9
	v_pk_mov_b32 v[12:13], v[4:5], v[12:13] op_sel:[1,0]
	v_mov_b32_e32 v18, v14
	v_pk_add_f32 v[10:11], v[10:11], v[12:13] neg_lo:[0,1] neg_hi:[0,1]
	v_mov_b32_e32 v15, v9
	v_pk_add_f32 v[4:5], v[6:7], v[10:11] neg_lo:[0,1] neg_hi:[0,1]
	s_movk_i32 s3, 0x204
	v_pk_add_f32 v[6:7], v[18:19], v[4:5]
	s_mov_b32 s8, 0x7f800000
	v_pk_add_f32 v[10:11], v[6:7], v[6:7] op_sel:[0,1] op_sel_hi:[1,0]
	v_mov_b32_e32 v3, 0
	v_pk_add_f32 v[8:9], v[8:9], v[10:11] op_sel:[1,0] op_sel_hi:[0,1]
	v_mov_b32_e32 v7, v8
	v_pk_add_f32 v[12:13], v[6:7], v[14:15] neg_lo:[0,1] neg_hi:[0,1]
	v_mov_b32_e32 v5, v10
	v_sub_f32_e32 v6, v6, v12
	v_pk_add_f32 v[4:5], v[4:5], v[12:13] neg_lo:[0,1] neg_hi:[0,1]
	v_sub_f32_e32 v6, v14, v6
	v_add_f32_e32 v4, v4, v6
	v_add_f32_e32 v4, v4, v5
	v_add_f32_e32 v5, v8, v4
	v_sub_f32_e32 v6, v5, v8
	v_sub_f32_e32 v4, v4, v6
	v_mul_f32_e32 v6, v1, v5
	v_fma_f32 v5, v1, v5, -v6
	v_fmac_f32_e32 v5, v1, v4
	v_add_f32_e32 v4, v6, v5
	v_cmp_class_f32_e64 vcc, v6, s3
	v_sub_f32_e32 v7, v4, v6
	v_sub_f32_e32 v5, v5, v7
	v_cndmask_b32_e32 v4, v4, v6, vcc
	v_mov_b32_e32 v6, 0x37000000
	v_cmp_eq_f32_e32 vcc, s4, v4
	v_cmp_gt_u32_e64 s[10:11], 32, v2
	v_lshrrev_b32_e32 v26, 6, v2
	v_cndmask_b32_e32 v6, 0, v6, vcc
	v_sub_f32_e32 v7, v4, v6
	v_mul_f32_e32 v8, 0x3fb8aa3b, v7
	v_fma_f32 v9, v7, s5, -v8
	v_rndne_f32_e32 v10, v8
	v_fmamk_f32 v9, v7, 0x32a5705f, v9
	v_sub_f32_e32 v8, v8, v10
	v_add_f32_e32 v8, v8, v9
	v_exp_f32_e32 v8, v8
	v_cvt_i32_f32_e32 v9, v10
	v_cmp_neq_f32_e64 vcc, |v4|, s8
	s_mov_b32 s5, 0xc2ce8ed0
	v_lshlrev_b32_e32 v20, 3, v17
	v_cndmask_b32_e32 v4, 0, v5, vcc
	v_ldexp_f32 v5, v8, v9
	v_cmp_ngt_f32_e32 vcc, s5, v7
	v_add_f32_e32 v4, v6, v4
	v_mov_b32_e32 v6, 0x7f800000
	v_cndmask_b32_e32 v5, 0, v5, vcc
	v_cmp_nlt_f32_e32 vcc, s4, v7
	v_mov_b32_e32 v21, v3
	v_readlane_b32 s58, v252, 0
	v_cndmask_b32_e32 v5, v6, v5, vcc
	v_fma_f32 v4, v5, v4, v5
	v_cmp_class_f32_e64 vcc, v5, s3
	s_movk_i32 s3, 0x104
	v_cmp_gt_u32_e64 s[6:7], 32, v17
	v_cndmask_b32_e32 v4, v4, v5, vcc
	v_and_b32_e32 v5, 0x7fffffff, v4
	v_div_scale_f32 v6, s[4:5], v5, v5, 1.0
	v_rcp_f32_e32 v7, v6
	v_div_scale_f32 v5, vcc, 1.0, v5, 1.0
	v_cmp_eq_u32_e64 s[4:5], 0, v17
	v_fma_f32 v8, -v6, v7, 1.0
	v_fmac_f32_e32 v7, v8, v7
	v_mul_f32_e32 v8, v5, v7
	v_fma_f32 v9, -v6, v8, v5
	v_fmac_f32_e32 v8, v9, v7
	v_fma_f32 v5, -v6, v8, v5
	v_div_fmas_f32 v5, v5, v7, v8
	v_div_fixup_f32 v4, v5, |v4|, 1.0
	v_cmp_neq_f32_e32 vcc, s8, v1
	v_lshlrev_b32_e32 v1, 1, v2
	v_and_b32_e32 v22, 62, v1
	v_cndmask_b32_e32 v27, 0, v4, vcc
	v_lshrrev_b32_e32 v4, 5, v2
	v_add_u32_e32 v1, 8, v4
	v_lshlrev_b32_e32 v5, 2, v4
	v_mad_u32_u24 v28, v22, s3, v5
	v_lshlrev_b32_e32 v5, 2, v1
	v_add_u32_e32 v12, 16, v4
	v_mad_u32_u24 v29, v22, s3, v5
	v_add_u32_e32 v5, 24, v4
	v_lshlrev_b32_e32 v13, 2, v12
	v_mad_u32_u24 v30, v22, s3, v13
	v_lshlrev_b32_e32 v13, 2, v5
	v_add_u32_e32 v14, 32, v4
	v_mad_u32_u24 v31, v22, s3, v13
	v_add_u32_e32 v13, 40, v4
	v_lshlrev_b32_e32 v15, 2, v14
	v_mad_u32_u24 v32, v22, s3, v15
	v_lshlrev_b32_e32 v15, 2, v13
	v_add_u32_e32 v16, 48, v4
	v_mad_u32_u24 v33, v22, s3, v15
	v_add_u32_e32 v15, 56, v4
	v_lshlrev_b32_e32 v18, 2, v16
	v_lshl_add_u64 v[8:9], v[2:3], 2, s[88:89]
	v_lshlrev_b32_e32 v2, 4, v17
	v_mad_u32_u24 v34, v22, s3, v18
	v_lshlrev_b32_e32 v18, 2, v15
	v_lshl_add_u64 v[10:11], s[64:65], 0, v[2:3]
	v_mad_u32_u24 v35, v22, s3, v18
	v_lshl_add_u64 v[18:19], s[60:61], 0, v[2:3]
	v_mul_lo_u32 v2, v26, s3
	v_lshl_add_u32 v36, v17, 2, v2
	v_mbcnt_lo_u32_b32 v2, -1, 0
	v_mbcnt_hi_u32_b32 v37, -1, v2
	v_and_b32_e32 v2, 64, v37
	v_lshl_add_u64 v[6:7], s[18:19], 0, v[20:21]
	v_lshl_add_u64 v[20:21], s[92:93], 0, v[20:21]
	s_movk_i32 s3, 0x7fff
	v_add_u32_e32 v38, 64, v2
	v_xor_b32_e32 v39, 32, v37
	v_xor_b32_e32 v40, 16, v37
	v_xor_b32_e32 v41, 8, v37
	v_xor_b32_e32 v42, 4, v37
	v_xor_b32_e32 v43, 2, v37
	v_xor_b32_e32 v44, 1, v37
	v_mov_b32_e32 v45, 0x3c0881c4
	v_mov_b32_e32 v46, 0xbab64f3b
	s_movk_i32 s26, 0x1000
	v_lshlrev_b32_e32 v22, 1, v22
	v_mov_b32_e32 v47, 1
	v_not_b32_e32 v48, 63
	v_not_b32_e32 v49, 31
	v_mov_b32_e32 v50, 0x7fc00000
	s_mov_b32 s27, s2
	v_readlane_b32 s59, v252, 1
	s_branch .LBB0_19

.LBB0_23:
	s_or_b64 exec, exec, s[8:9]
	v_lshl_add_u32 v2, s12, 2, v26
	v_lshlrev_b64 v[24:25], 12, v[2:3]
	v_lshl_add_u64 v[68:69], v[18:19], 0, v[24:25]
	v_readlane_b32 s14, v252, 44
	s_nop 3
	s_cmp_eq_u32 s14, 1
	s_cbranch_scc1 .Lp0_have
	v_mov_b64_e32 v[116:117], v[68:69]
	v_lshl_add_u64 v[112:113], v[2:3], 2, s[62:63]
	global_load_dwordx4 v[80:83], v[10:11], off
	global_load_dwordx4 v[84:87], v[116:117], off
	global_load_dwordx4 v[88:91], v[116:117], off offset:1024
	global_load_dwordx4 v[92:95], v[10:11], off offset:1024
	global_load_dwordx4 v[96:99], v[116:117], off offset:2048
	global_load_dwordx4 v[100:103], v[10:11], off offset:2048
	global_load_dwordx4 v[104:107], v[116:117], off offset:3072
	global_load_dwordx4 v[108:111], v[10:11], off offset:3072
	global_load_dword v114, v[112:113], off
.Lp0_have:
	s_waitcnt vmcnt(0)
	v_mov_b64_e32 v[52:53], v[80:81]
	v_mov_b64_e32 v[54:55], v[82:83]
	v_mov_b64_e32 v[56:57], v[84:85]
	v_mov_b64_e32 v[58:59], v[86:87]
	v_lshlrev_b64 v[24:25], 11, v[2:3]
	v_lshl_add_u64 v[24:25], v[20:21], 0, v[24:25]
	v_cmp_lt_i32_e32 vcc, v39, v38
	v_pk_mul_f32 v[54:55], v[58:59], v[54:55]
	v_pk_mul_f32 v[52:53], v[56:57], v[52:53]
	v_and_b32_sdwa v60, v55, v47 dst_sel:DWORD dst_unused:UNUSED_PAD src0_sel:WORD_1 src1_sel:DWORD
	v_and_b32_sdwa v51, v52, v47 dst_sel:DWORD dst_unused:UNUSED_PAD src0_sel:WORD_1 src1_sel:DWORD
	v_and_b32_sdwa v61, v53, v47 dst_sel:DWORD dst_unused:UNUSED_PAD src0_sel:WORD_1 src1_sel:DWORD
	v_and_b32_sdwa v23, v54, v47 dst_sel:DWORD dst_unused:UNUSED_PAD src0_sel:WORD_1 src1_sel:DWORD
	v_add3_u32 v51, v52, v51, s3
	v_add3_u32 v52, v55, v60, s3
	v_add3_u32 v53, v53, v61, s3
	v_add3_u32 v23, v54, v23, s3
	v_and_b32_e32 v52, 0xffff0000, v52
	v_and_b32_e32 v54, 0xffff0000, v53
	v_or_b32_sdwa v53, v52, v23 dst_sel:DWORD dst_unused:UNUSED_PAD src0_sel:DWORD src1_sel:WORD_1
	v_or_b32_sdwa v52, v54, v51 dst_sel:DWORD dst_unused:UNUSED_PAD src0_sel:DWORD src1_sel:WORD_1
	global_store_dwordx2 v[24:25], v[52:53], off
	v_mov_b64_e32 v[52:53], v[88:89]
	v_mov_b64_e32 v[54:55], v[90:91]
	s_nop 0
	v_mov_b64_e32 v[60:61], v[92:93]
	v_mov_b64_e32 v[62:63], v[94:95]
	v_pk_mul_f32 v[56:57], v[56:57], v[56:57]
	v_pk_mul_f32 v[58:59], v[58:59], v[58:59]
	v_add_f32_e32 v56, v56, v57
	v_add_f32_e32 v56, v56, v58
	v_add_f32_e32 v56, v56, v59
	v_pk_mul_f32 v[62:63], v[54:55], v[62:63]
	v_pk_mul_f32 v[60:61], v[52:53], v[60:61]
	v_and_b32_sdwa v64, v63, v47 dst_sel:DWORD dst_unused:UNUSED_PAD src0_sel:WORD_1 src1_sel:DWORD
	v_and_b32_sdwa v51, v60, v47 dst_sel:DWORD dst_unused:UNUSED_PAD src0_sel:WORD_1 src1_sel:DWORD
	v_and_b32_sdwa v65, v61, v47 dst_sel:DWORD dst_unused:UNUSED_PAD src0_sel:WORD_1 src1_sel:DWORD
	v_and_b32_sdwa v23, v62, v47 dst_sel:DWORD dst_unused:UNUSED_PAD src0_sel:WORD_1 src1_sel:DWORD
	v_add3_u32 v51, v60, v51, s3
	v_add3_u32 v60, v63, v64, s3
	v_add3_u32 v61, v61, v65, s3
	v_add3_u32 v23, v62, v23, s3
	v_and_b32_e32 v60, 0xffff0000, v60
	v_and_b32_e32 v62, 0xffff0000, v61
	v_or_b32_sdwa v61, v60, v23 dst_sel:DWORD dst_unused:UNUSED_PAD src0_sel:DWORD src1_sel:WORD_1
	v_or_b32_sdwa v60, v62, v51 dst_sel:DWORD dst_unused:UNUSED_PAD src0_sel:DWORD src1_sel:WORD_1
	global_store_dwordx2 v[24:25], v[60:61], off offset:512
	v_mov_b64_e32 v[60:61], v[96:97]
	v_mov_b64_e32 v[62:63], v[98:99]
	s_nop 0
	v_mov_b64_e32 v[64:65], v[100:101]
	v_mov_b64_e32 v[66:67], v[102:103]
	v_pk_mul_f32 v[52:53], v[52:53], v[52:53]
	v_pk_mul_f32 v[54:55], v[54:55], v[54:55]
	v_add_f32_e32 v52, v52, v53
	v_add_f32_e32 v52, v52, v54
	v_add_f32_e32 v52, v52, v55
	v_add_f32_e32 v56, v56, v52
	v_pk_mul_f32 v[54:55], v[60:61], v[60:61]
	v_pk_mul_f32 v[66:67], v[62:63], v[66:67]
	v_pk_mul_f32 v[64:65], v[60:61], v[64:65]
	v_and_b32_sdwa v70, v67, v47 dst_sel:DWORD dst_unused:UNUSED_PAD src0_sel:WORD_1 src1_sel:DWORD
	v_and_b32_sdwa v51, v64, v47 dst_sel:DWORD dst_unused:UNUSED_PAD src0_sel:WORD_1 src1_sel:DWORD
	v_and_b32_sdwa v71, v65, v47 dst_sel:DWORD dst_unused:UNUSED_PAD src0_sel:WORD_1 src1_sel:DWORD
	v_and_b32_sdwa v23, v66, v47 dst_sel:DWORD dst_unused:UNUSED_PAD src0_sel:WORD_1 src1_sel:DWORD
	v_add3_u32 v51, v64, v51, s3
	v_add3_u32 v64, v67, v70, s3
	v_add3_u32 v65, v65, v71, s3
	v_add3_u32 v23, v66, v23, s3
	v_and_b32_e32 v64, 0xffff0000, v64
	v_and_b32_e32 v66, 0xffff0000, v65
	v_or_b32_sdwa v65, v64, v23 dst_sel:DWORD dst_unused:UNUSED_PAD src0_sel:DWORD src1_sel:WORD_1
	v_or_b32_sdwa v64, v66, v51 dst_sel:DWORD dst_unused:UNUSED_PAD src0_sel:DWORD src1_sel:WORD_1
	global_store_dwordx2 v[24:25], v[64:65], off offset:1024
	v_mov_b64_e32 v[64:65], v[104:105]
	v_mov_b64_e32 v[66:67], v[106:107]
	s_nop 0
	v_mov_b64_e32 v[68:69], v[108:109]
	v_mov_b64_e32 v[70:71], v[110:111]
	v_mov_b32_e32 v118, v114
	s_load_dword s12, s[0:1], 0x1b8
	s_waitcnt lgkmcnt(0)
	s_add_i32 s13, s27, s12
	s_cmpk_lt_i32 s13, 0x3720
	s_cbranch_scc0 .Lp0_pf_none
	s_lshl_b32 s14, s12, 14
	s_mov_b32 s15, 0
	v_lshl_add_u64 v[116:117], v[116:117], 0, s[14:15]
	s_lshl_b32 s14, s12, 4
	v_lshl_add_u64 v[112:113], v[112:113], 0, s[14:15]
	global_load_dwordx4 v[80:83], v[10:11], off
	global_load_dwordx4 v[84:87], v[116:117], off
	global_load_dwordx4 v[88:91], v[116:117], off offset:1024
	global_load_dwordx4 v[92:95], v[10:11], off offset:1024
	global_load_dwordx4 v[96:99], v[116:117], off offset:2048
	global_load_dwordx4 v[100:103], v[10:11], off offset:2048
	global_load_dwordx4 v[104:107], v[116:117], off offset:3072
	global_load_dwordx4 v[108:111], v[10:11], off offset:3072
	global_load_dword v114, v[112:113], off
	v_writelane_b32 v252, 1, 44
	s_branch .Lp0_pf_done
.Lp0_pf_none:
	v_writelane_b32 v252, 0, 44
.Lp0_pf_done:
	v_pk_mul_f32 v[52:53], v[62:63], v[62:63]
	v_add_f32_e32 v54, v54, v55
	v_add_f32_e32 v52, v54, v52
	v_add_f32_e32 v52, v52, v53
	v_add_f32_e32 v56, v56, v52
	v_cndmask_b32_e32 v23, v37, v39, vcc
	v_lshlrev_b32_e32 v23, 2, v23
	v_cmp_lt_i32_e32 vcc, v40, v38
	v_pk_mul_f32 v[54:55], v[64:65], v[64:65]
	v_pk_mul_f32 v[52:53], v[66:67], v[66:67]
	v_add_f32_e32 v54, v54, v55
	v_add_f32_e32 v52, v54, v52
	v_add_f32_e32 v52, v52, v53
	v_add_f32_e32 v52, v56, v52
	ds_bpermute_b32 v23, v23, v52
	v_cndmask_b32_e32 v51, v37, v40, vcc
	v_lshlrev_b32_e32 v51, 2, v51
	v_cmp_lt_i32_e32 vcc, v41, v38
	s_waitcnt lgkmcnt(0)
	v_add_f32_e32 v23, v52, v23
	ds_bpermute_b32 v51, v51, v23
	v_cndmask_b32_e32 v72, v37, v41, vcc
	v_lshlrev_b32_e32 v52, 2, v72
	v_cmp_lt_i32_e32 vcc, v42, v38
	s_waitcnt lgkmcnt(0)
	v_add_f32_e32 v23, v23, v51
	ds_bpermute_b32 v51, v52, v23
	v_cndmask_b32_e32 v53, v37, v42, vcc
	v_lshlrev_b32_e32 v57, 2, v53
	v_cmp_lt_i32_e32 vcc, v43, v38
	v_pk_mul_f32 v[52:53], v[66:67], v[70:71]
	s_waitcnt lgkmcnt(0)
	v_add_f32_e32 v23, v23, v51
	ds_bpermute_b32 v51, v57, v23
	v_cndmask_b32_e32 v54, v37, v43, vcc
	v_lshlrev_b32_e32 v58, 2, v54
	v_cmp_lt_i32_e32 vcc, v44, v38
	v_pk_mul_f32 v[54:55], v[64:65], v[68:69]
	s_waitcnt lgkmcnt(0)
	v_add_f32_e32 v23, v23, v51
	ds_bpermute_b32 v51, v58, v23
	v_cndmask_b32_e32 v56, v37, v44, vcc
	v_and_b32_sdwa v60, v53, v47 dst_sel:DWORD dst_unused:UNUSED_PAD src0_sel:WORD_1 src1_sel:DWORD
	v_and_b32_sdwa v61, v55, v47 dst_sel:DWORD dst_unused:UNUSED_PAD src0_sel:WORD_1 src1_sel:DWORD
	v_and_b32_sdwa v59, v52, v47 dst_sel:DWORD dst_unused:UNUSED_PAD src0_sel:WORD_1 src1_sel:DWORD
	s_waitcnt lgkmcnt(0)
	v_add_f32_e32 v23, v23, v51
	v_lshlrev_b32_e32 v51, 2, v56
	ds_bpermute_b32 v51, v51, v23
	v_and_b32_sdwa v57, v54, v47 dst_sel:DWORD dst_unused:UNUSED_PAD src0_sel:WORD_1 src1_sel:DWORD
	v_add3_u32 v53, v53, v60, s3
	v_add3_u32 v55, v55, v61, s3
	v_add3_u32 v54, v54, v57, s3
	v_add3_u32 v52, v52, v59, s3
	v_and_b32_e32 v53, 0xffff0000, v53
	v_and_b32_e32 v55, 0xffff0000, v55
	v_or_b32_sdwa v53, v53, v52 dst_sel:DWORD dst_unused:UNUSED_PAD src0_sel:DWORD src1_sel:WORD_1
	v_or_b32_sdwa v52, v55, v54 dst_sel:DWORD dst_unused:UNUSED_PAD src0_sel:DWORD src1_sel:WORD_1
	global_store_dwordx2 v[24:25], v[52:53], off offset:1536
	s_and_saveexec_b64 s[8:9], s[4:5]
	s_cbranch_execz .LBB0_25
	v_lshl_add_u64 v[24:25], v[2:3], 2, s[16:17]
	v_add_co_u32_e32 v52, vcc, 0x20000, v24
	s_waitcnt lgkmcnt(0)
	v_add_f32_e32 v23, v23, v51
	v_addc_co_u32_e32 v53, vcc, 0, v25, vcc
	global_store_dword v[52:53], v3, off
	v_add_co_u32_e32 v52, vcc, 0x40000, v24
	global_store_dword v[24:25], v23, off
	s_nop 0
	v_addc_co_u32_e32 v53, vcc, 0, v25, vcc
	v_add_co_u32_e32 v24, vcc, 0x60000, v24
	global_store_dword v[52:53], v3, off
	s_nop 0
	v_addc_co_u32_e32 v25, vcc, 0, v25, vcc
	global_store_dword v[24:25], v3, off
.LBB0_25:
	s_or_b64 exec, exec, s[8:9]
	s_and_saveexec_b64 s[22:23], s[6:7]
	s_cbranch_execz .LBB0_31
	v_lshl_add_u64 v[24:25], v[2:3], 2, s[62:63]
	v_mov_b32_e32 v23, v118
	s_brev_b32 s8, 18
	v_cvt_f32_i32_e32 v23, v23
	v_mul_f32_e32 v23, v27, v23
	v_and_b32_e32 v24, 0x7fffffff, v23
	v_cmp_nlt_f32_e64 s[8:9], |v23|, s8
	s_and_saveexec_b64 s[12:13], s[8:9]
	s_xor_b64 s[24:25], exec, s[12:13]
	s_cbranch_execz .LBB0_28
	v_lshrrev_b32_e32 v25, 23, v24
	v_add_u32_e32 v25, 0xffffff88, v25
	v_cmp_lt_u32_e32 vcc, 63, v25
	s_mov_b32 s14, 0xfe5163ab
	v_mov_b32_e32 v55, v3
	s_waitcnt lgkmcnt(0)
	v_cndmask_b32_e32 v51, 0, v48, vcc
	v_add_u32_e32 v25, v51, v25
	v_cmp_lt_u32_e64 s[8:9], 31, v25
	v_mov_b32_e32 v57, v3
	v_mov_b32_e32 v59, v3
	v_cndmask_b32_e64 v51, 0, v49, s[8:9]
	v_add_u32_e32 v25, v51, v25
	v_cmp_lt_u32_e64 s[12:13], 31, v25
	v_mov_b32_e32 v61, v3
	v_mov_b32_e32 v63, v3
	v_cndmask_b32_e64 v51, 0, v49, s[12:13]
	v_add_u32_e32 v25, v51, v25
	v_and_b32_e32 v51, 0x7fffff, v24
	v_or_b32_e32 v51, 0x800000, v51
	v_mad_u64_u32 v[52:53], s[14:15], v51, s14, 0
	v_mov_b32_e32 v54, v53
	s_mov_b32 s14, 0x3c439041
	v_mad_u64_u32 v[54:55], s[14:15], v51, s14, v[54:55]
	v_mov_b32_e32 v56, v55
	s_mov_b32 s14, 0xdb629599
	v_mad_u64_u32 v[56:57], s[14:15], v51, s14, v[56:57]
	v_mov_b32_e32 v58, v57
	s_mov_b32 s14, 0xf534ddc0
	v_mad_u64_u32 v[58:59], s[14:15], v51, s14, v[58:59]
	v_mov_b32_e32 v60, v59
	s_mov_b32 s14, 0xfc2757d1
	v_mad_u64_u32 v[60:61], s[14:15], v51, s14, v[60:61]
	v_mov_b32_e32 v62, v61
	s_mov_b32 s14, 0x4e441529
	v_mad_u64_u32 v[62:63], s[14:15], v51, s14, v[62:63]
	v_mov_b32_e32 v64, v63
	v_mov_b32_e32 v65, v3
	s_mov_b32 s14, 0xa2f9836e
	v_mad_u64_u32 v[64:65], s[14:15], v51, s14, v[64:65]
	v_cndmask_b32_e32 v53, v62, v58, vcc
	v_cndmask_b32_e32 v51, v64, v60, vcc
	v_cndmask_b32_e32 v57, v65, v62, vcc
	v_cndmask_b32_e64 v55, v51, v53, s[8:9]
	v_cndmask_b32_e64 v51, v57, v51, s[8:9]
	v_cndmask_b32_e32 v57, v60, v56, vcc
	v_cndmask_b32_e64 v53, v53, v57, s[8:9]
	v_sub_u32_e32 v59, 32, v25
	v_cmp_eq_u32_e64 s[14:15], 0, v25
	v_cndmask_b32_e32 v25, v58, v54, vcc
	v_cndmask_b32_e64 v51, v51, v55, s[12:13]
	v_cndmask_b32_e64 v55, v55, v53, s[12:13]
	v_cndmask_b32_e64 v54, v57, v25, s[8:9]
	v_alignbit_b32 v60, v51, v55, v59
	v_cndmask_b32_e64 v53, v53, v54, s[12:13]
	v_cndmask_b32_e64 v51, v60, v51, s[14:15]
	v_alignbit_b32 v57, v55, v53, v59
	v_cndmask_b32_e32 v52, v56, v52, vcc
	v_cndmask_b32_e64 v55, v57, v55, s[14:15]
	v_bfe_u32 v60, v51, 29, 1
	v_cndmask_b32_e64 v25, v25, v52, s[8:9]
	v_alignbit_b32 v57, v51, v55, 30
	v_sub_u32_e32 v61, 0, v60
	v_cndmask_b32_e64 v25, v54, v25, s[12:13]
	v_xor_b32_e32 v57, v57, v61
	v_alignbit_b32 v52, v53, v25, v59
	v_cndmask_b32_e64 v52, v52, v53, s[14:15]
	v_ffbh_u32_e32 v54, v57
	v_alignbit_b32 v53, v55, v52, 30
	v_min_u32_e32 v54, 32, v54
	v_alignbit_b32 v25, v52, v25, 30
	v_xor_b32_e32 v53, v53, v61
	v_sub_u32_e32 v55, 31, v54
	v_xor_b32_e32 v25, v25, v61
	v_alignbit_b32 v56, v57, v53, v55
	v_alignbit_b32 v25, v53, v25, v55
	v_alignbit_b32 v52, v56, v25, 9
	v_ffbh_u32_e32 v53, v52
	v_min_u32_e32 v53, 32, v53
	v_lshrrev_b32_e32 v58, 29, v51
	v_not_b32_e32 v55, v53
	v_alignbit_b32 v25, v52, v25, v55
	v_lshlrev_b32_e32 v52, 31, v58
	v_or_b32_e32 v55, 0x33000000, v52
	v_add_lshl_u32 v53, v53, v54, 23
	v_lshrrev_b32_e32 v25, 9, v25
	v_sub_u32_e32 v53, v55, v53
	v_or_b32_e32 v52, 0.5, v52
	v_lshlrev_b32_e32 v54, 23, v54
	v_or_b32_e32 v25, v53, v25
	v_lshrrev_b32_e32 v53, 9, v56
	v_sub_u32_e32 v52, v52, v54
	v_or_b32_e32 v52, v53, v52
	v_mul_f32_e32 v53, 0x3fc90fda, v52
	s_mov_b32 s8, 0x3fc90fda
	v_fma_f32 v54, v52, s8, -v53
	v_fmac_f32_e32 v54, 0x33a22168, v52
	v_fmac_f32_e32 v54, 0x3fc90fda, v25
	v_lshrrev_b32_e32 v51, 30, v51
	v_add_f32_e32 v25, v53, v54
	v_add_u32_e32 v51, v60, v51
